# P5 epilogue pipelined; P8: half the workgroups (bit 3 of id) run their K-slice unit first (epilogue bursts of the two halves interleave); P4: half of the two-unit workgroups do their weight copies bef
# baseline (speedup 1.0000x reference)
;     __device__ __forceinline__ const char* a_base(const Unit& u) const { return (const char*)(A + (size_t)u.pm * BM * lda + (agrp ? (u.pn >> 1) * 256 : 0) + u.k0); }
;     __device__ __forceinline__ const char* a2_base(const Unit& u) const { return (const char*)(A2 + (size_t)u.pm * BM * lda) - (size_t)nt0 * (BK * 2); }
;     __host__ __device__ void init(int G_, int c_, int K) { StaticOrder::init(64 * BM, 2048, G_, c_, K); nch = K / 128; }
; #define PG8_STAGE(bufoff, gbase, voff) do { _Pragma("unroll") for (int _i = 0; _i < 2; ++_i) \
;         __builtin_amdgcn_global_load_lds((const unsigned*)((const char*)(gbase) + (voff)[_i]), (PG8_LAS unsigned*)(lds + (bufoff) + ldsw + _i * 8192), 16, 0, 0); } while (0)
; #define PG8_WAIT_V(n) asm volatile("s_waitcnt vmcnt(" #n ")" ::: "memory")
; #define PG8_BAR __builtin_amdgcn_s_barrier()
; template <class Epi, class Sched, bool ALIGN_EPI = false, bool SP2 = false>
; __device__ __forceinline__ void gemm_phase(PG8_LAS unsigned char* lds, const Gemm g, const Sched& S, const Epi& E) {
;     ...
;     const char* cA = g.a_base(cur); const char* cB = g.b_base(cur);
;     const char* cA2 = cA; if constexpr (Epi::HAS_MID) cA2 = g.a2_base(cur);
;     S.a_ready(cur);
;     if constexpr (SP2) {
;         PG8_STAGE(PG8_SB(0, 0), cB, voffB); PG8_STAGE(PG8_SB(0, 1), cB + hstepB, voffB); PG8_STAGE(PG8_SA(0, 0), cA, voffA); PG8_STAGE(PG8_SA(0, 1), cA + hstepA, voffA);
;         if (wr == 1) PG8_BAR;
;         PG8_WAIT_V(2); PG8_BAR;
; __global__ void __launch_bounds__(512, 2) fwd_kernel(Params P) {
;     ...
;         pg8::Gemm g{Db, WsbT, 1024, 1280, 1280, 1, Ob, 4}; pg8::StaticOrder S; S.init(NTOK, DM, G, bx, 1280);
;         EpiMix E{SGA, SGB, Mb};
;         pg8::gemm_phase<EpiMix, pg8::StaticOrder, true, true>(lds, g, S, E);
.LBB0_858:
	s_or_b64 exec, exec, s[4:5]
	s_mov_b64 s[4:5], s[0:1]
	s_waitcnt lgkmcnt(0)
	s_barrier
	s_bitcmp1_b32 s2, 3
	s_cselect_b32 s99, 1, 0
	s_cmpk_eq_u32 s48, 0x100
	s_cselect_b32 s99, s99, 0
	s_cmpk_gt_u32 s2, 31
	s_cselect_b32 s99, s99, 0
.Lp4_entry:
	s_mov_b64 s[4:5], s[0:1]
	v_mov_b32_e32 v208, v254
	s_load_dwordx2 s[10:11], s[4:5], 0xb0
	s_load_dwordx2 s[12:13], s[4:5], 0x68
	s_load_dwordx2 s[8:9], s[4:5], 0x90
	v_mov_b32_e32 v10, v254
	s_cmp_eq_u32 s99, 1
	s_cbranch_scc1 .LBB0_883
	s_cmpk_gt_i32 s2, 0x21f
	v_readfirstlane_b32 s6, v10
	s_cbranch_scc1 .LBB0_883
	v_lshlrev_b32_e32 v0, 4, v10
	v_add_u32_e32 v1, 0x2000, v0
	v_ashrrev_i32_e32 v2, 31, v1
	v_lshrrev_b32_e32 v2, 22, v2
	v_add_u32_e32 v2, v1, v2
	v_ashrrev_i32_e32 v8, 10, v2
	v_mul_i32_i24_e32 v2, 0x400, v8
	v_sub_u32_e32 v1, v1, v2
	v_lshrrev_b32_e32 v2, 4, v1
	v_bitop3_b32 v1, v2, v1, 32 bitop3:0x6c
	v_ashrrev_i32_e32 v2, 31, v1
	v_lshrrev_b32_e32 v2, 26, v2
	v_add_u32_e32 v2, v1, v2
	v_lshlrev_b32_e32 v3, 3, v8
	v_ashrrev_i32_e32 v9, 6, v2
	v_and_b32_e32 v3, -16, v3
	v_add_u32_e32 v3, v9, v3
	v_and_b32_e32 v4, 3, v9
	s_mov_b32 s4, 0xffffe0
	v_lshrrev_b32_e32 v5, 2, v3
	v_lshlrev_b32_e32 v6, 1, v3
	v_and_b32_e32 v2, 0xc0, v2
	v_and_or_b32 v4, v3, s4, v4
	v_and_b32_e32 v5, 4, v5
	v_and_b32_e32 v6, 24, v6
	v_sub_u32_e32 v1, v1, v2
	v_mov_b32_e32 v2, 1
	v_or3_b32 v4, v4, v5, v6
	v_lshlrev_b32_e32 v5, 5, v8
	v_ashrrev_i16_sdwa v1, v2, sext(v1) dst_sel:DWORD dst_unused:UNUSED_PAD src0_sel:DWORD src1_sel:BYTE_0
	v_and_b32_e32 v5, 32, v5
	v_bfe_i32 v11, v1, 0, 16
	v_mul_u32_u24_e32 v4, 0x500, v4
	v_add_u32_e32 v1, v5, v11
	v_lshlrev_b32_e32 v3, 11, v3
	v_add_lshl_u32 v160, v4, v1, 1
	v_lshl_add_u32 v162, v1, 1, v3
	v_bfe_i32 v1, v10, 27, 1
	v_lshrrev_b32_e32 v1, 22, v1
	v_add_u32_e32 v1, v0, v1
	v_and_b32_e32 v1, 0xfffffc00, v1
	v_sub_u32_e32 v0, v0, v1
	v_lshrrev_b32_e32 v1, 4, v0
	v_ashrrev_i32_e32 v3, 31, v10
	v_bitop3_b32 v0, v1, v0, 32 bitop3:0x6c
	v_lshrrev_b32_e32 v3, 26, v3
	v_ashrrev_i32_e32 v1, 31, v0
	v_add_u32_e32 v3, v10, v3
	s_waitcnt lgkmcnt(0)
	s_add_u32 s45, s10, 0x2000000
	v_lshrrev_b32_e32 v1, 26, v1
	v_ashrrev_i32_e32 v13, 6, v3
	s_addc_u32 s47, s11, 0
	v_add_u32_e32 v1, v0, v1
	v_lshlrev_b32_e32 v3, 3, v13
	s_add_u32 s68, s10, 0x9200000
	v_ashrrev_i32_e32 v12, 6, v1
	v_and_b32_e32 v3, -16, v3
	s_addc_u32 s69, s11, 0
	v_add_u32_e32 v3, v12, v3
	v_and_b32_e32 v4, 3, v12
	s_ashr_i32 s71, s2, 31
	v_and_or_b32 v4, v3, s4, v4
	s_lshr_b32 s4, s71, 29
	s_add_i32 s4, s2, s4
	s_ashr_i32 s7, s6, 6
	s_and_b32 s5, s4, -8
	s_ashr_i32 s14, s6, 8
	s_lshl_b32 s70, s7, 10
	s_sub_i32 s5, s2, s5
	s_cmp_lt_i32 s5, 0
	s_movk_i32 s72, 0x45
	s_cselect_b32 s15, s72, 0x44
	s_mul_i32 s5, s5, s15
	s_ashr_i32 s4, s4, 3
	s_add_i32 s4, s5, s4
	s_ashr_i32 s5, s4, 31
	s_lshr_b32 s5, s5, 26
	s_add_i32 s5, s4, s5
	v_lshrrev_b32_e32 v5, 2, v3
	v_lshlrev_b32_e32 v6, 1, v3
	v_and_b32_e32 v1, 0xc0, v1
	s_ashr_i32 s5, s5, 6
	v_and_b32_e32 v5, 4, v5
	v_and_b32_e32 v6, 24, v6
	v_sub_u32_e32 v0, v0, v1
	s_lshl_b32 s15, s5, 3
	v_or3_b32 v4, v4, v5, v6
	v_lshlrev_b32_e32 v5, 5, v13
	v_ashrrev_i16_sdwa v0, v2, sext(v0) dst_sel:DWORD dst_unused:UNUSED_PAD src0_sel:DWORD src1_sel:BYTE_0
	s_sub_i32 s16, 0x44, s15
	s_lshl_b32 s5, s5, 6
	v_and_b32_e32 v5, 32, v5
	v_bfe_i32 v14, v0, 0, 16
	s_min_u32 s17, s16, 8
	s_sub_i32 s18, s4, s5
	v_mul_u32_u24_e32 v4, 0x500, v4
	v_add_u32_e32 v0, v5, v14
	v_lshlrev_b32_e32 v1, 11, v3
	s_sext_i32_i8 s4, s18
	v_cvt_f32_ubyte0_e32 v3, s17
	v_add_lshl_u32 v164, v4, v0, 1
	v_cvt_f32_i32_e32 v2, s4
	v_rcp_iflag_f32_e32 v4, v3
	v_lshl_add_u32 v166, v0, 1, v1
	s_ashr_i32 s4, s4, 30
	s_or_b32 s16, s4, 1
	v_mul_f32_e32 v0, v2, v4
	v_trunc_f32_e32 v0, v0
	v_fma_f32 v1, -v0, v3, v2
	v_cvt_i32_f32_e32 v0, v0
	v_cmp_ge_f32_e64 s[4:5], |v1|, v3
	s_and_b64 s[4:5], s[4:5], exec
	s_cselect_b32 s4, s16, 0
	v_readfirstlane_b32 s5, v0
	s_add_i32 s16, s5, s4
	s_mul_i32 s4, s16, s17
	s_sub_i32 s4, s18, s4
	s_sext_i32_i8 s4, s4
	s_sext_i32_i8 s90, s16
	s_add_i32 s60, s15, s4
	s_lshl_b32 s4, s90, 7
	s_ashr_i32 s61, s60, 31
	s_and_b32 s18, s4, 0xffffff00
	s_lshl_b64 s[4:5], s[60:61], 18
	s_lshl_b64 s[20:21], s[60:61], 19
	s_add_u32 s15, s68, s20
	s_addc_u32 s20, s69, s21
	s_bfe_i64 s[16:17], s[16:17], 0x80000
	s_mul_hi_i32 s17, s16, 0xa0000
	s_mul_i32 s16, s16, 0xa0000
	s_add_u32 s64, s45, s16
	s_addc_u32 s65, s47, s17
	s_add_i32 s61, s70, 0
	s_add_i32 m0, s61, 0x10000
	s_ashr_i32 s19, s18, 31
	global_load_lds_dwordx4 v164, s[64:65]
	s_add_i32 m0, s61, 0x12000
	s_lshl_b64 s[16:17], s[18:19], 1
	s_add_u32 s62, s15, s16
	s_addc_u32 s63, s20, s17
	s_add_u32 s16, s64, 0x50000
	global_load_lds_dwordx4 v160, s[64:65]
	s_addc_u32 s17, s65, 0
	s_add_i32 m0, s61, 0x14000
	s_add_i32 s73, s61, 0x2000
	global_load_lds_dwordx4 v164, s[16:17]
	s_add_i32 m0, s61, 0x16000
	v_mov_b32_e32 v169, 0
	global_load_lds_dwordx4 v160, s[16:17]
	s_mov_b32 m0, s61
	s_add_u32 s16, s62, 0x40000
	global_load_lds_dwordx4 v166, s[62:63]
	s_mov_b32 m0, s73
	s_addc_u32 s17, s63, 0
	s_add_i32 s75, s61, 0x4000
	global_load_lds_dwordx4 v162, s[62:63]
	s_mov_b32 m0, s75
	s_add_i32 s76, s61, 0x6000
	global_load_lds_dwordx4 v166, s[16:17]
	s_mov_b32 m0, s76
	v_mov_b32_e32 v165, v169
	global_load_lds_dwordx4 v162, s[16:17]
	v_mov_b32_e32 v161, v169
	v_mov_b32_e32 v167, v169
	v_mov_b32_e32 v163, v169
	s_cmp_eq_u32 s14, 1
	s_mov_b32 s15, 0
	v_lshl_add_u64 v[6:7], s[64:65], 0, v[164:165]
	v_lshl_add_u64 v[4:5], s[64:65], 0, v[160:161]
	v_lshl_add_u64 v[0:1], s[62:63], 0, v[166:167]
	s_cselect_b64 s[16:17], -1, 0
	s_cmp_lg_u32 s14, 1
	v_lshl_add_u64 v[2:3], s[62:63], 0, v[162:163]
	s_cbranch_scc1 .LBB0_861
	s_barrier

; #define LAS __attribute__((address_space(3)))
; __global__ void __launch_bounds__(512, 2) fwd_kernel(Params P) {
;     ...
;     { const int nl = (G == 256) ? 224 : G, lb = (G == 256) ? bx - 32 : bx; constexpr int I_D = 88 * 64;
;       LAS float* scr = (LAS float*)(lds + wave * 16384);
;       if (lb >= 0) for (int it = lb * 8 + wave; it < I_D + 2048; it += nl * 8) { const int kb = it / 64, nb = it % 64;
;           if (it < I_D) transpose_item(w_down, 2048, kb * 64, nb * 32, WdT, DFF, nb * 32, scr, lane);
;           else transpose_item(w_out, 2048, (kb - 88) * 64, nb * 32, WoT, 2048, nb * 32, scr, lane); } }
.LBB0_883:
	s_cmp_eq_u32 s99, 2
	s_cbranch_scc1 .LBB0_895
	s_sub_i32 s6, s2, 32
	s_and_b64 s[4:5], s[50:51], exec
	s_cselect_b32 s4, s6, s2
	s_cmp_gt_i32 s4, -1
	s_cbranch_scc0 .LBB0_895
	s_lshl_b32 s4, s4, 3
	v_readlane_b32 s5, v255, 0
	s_add_i32 s14, s5, s4
	s_cmpk_gt_i32 s14, 0x1dff
	s_cbranch_scc1 .LBB0_895
	v_lshlrev_b32_e32 v1, 2, v208
	v_and_b32_e32 v2, 0x7c, v1
	v_lshlrev_b32_e32 v1, 3, v208
	v_mov_b32_e32 v3, 0
	v_and_b32_e32 v1, 56, v1
	v_lshlrev_b32_e32 v8, 1, v1
	v_mov_b32_e32 v9, v3
	s_waitcnt lgkmcnt(0)
	v_lshl_add_u64 v[12:13], s[10:11], 0, v[8:9]
	s_mov_b64 s[4:5], 0x2500000
	v_bfe_u32 v7, v208, 3, 3
	v_lshl_add_u64 v[8:9], v[12:13], 0, s[4:5]
	s_mov_b64 s[4:5], 0x5900000
	v_bfe_u32 v0, v208, 5, 1
	v_mul_u32_u24_e32 v10, 0x84, v1
	v_lshlrev_b32_e32 v1, 2, v7
	v_lshl_add_u64 v[12:13], v[12:13], 0, s[4:5]
	s_and_b64 s[4:5], s[50:51], exec
	v_lshl_add_u64 v[4:5], s[12:13], 0, v[2:3]
	v_add_u32_e32 v6, s3, v2
	s_movk_i32 s12, 0x84
	v_add3_u32 v16, s3, v10, v1
	v_or_b32_e32 v17, 8, v7
	v_or_b32_e32 v18, 16, v7
	v_or_b32_e32 v19, 24, v7
	v_lshl_add_u64 v[10:11], s[8:9], 0, v[2:3]
	s_cselect_b32 s3, 0x700, s46
	v_mov_b32_e32 v1, v0
	s_mov_b32 s5, 0
	s_movk_i32 s10, 0x1600
	s_branch .LBB0_887

; #define LAS __attribute__((address_space(3)))
; __global__ void __launch_bounds__(512, 2) fwd_kernel(Params P) {
;     ...
;     { const int nl = (G == 256) ? 224 : G, lb = (G == 256) ? bx - 32 : bx; constexpr int I_D = 88 * 64;
;       LAS float* scr = (LAS float*)(lds + wave * 16384);
;       if (lb >= 0) for (int it = lb * 8 + wave; it < I_D + 2048; it += nl * 8) { const int kb = it / 64, nb = it % 64;
;           if (it < I_D) transpose_item(w_down, 2048, kb * 64, nb * 32, WdT, DFF, nb * 32, scr, lane);
;           else transpose_item(w_out, 2048, (kb - 88) * 64, nb * 32, WoT, 2048, nb * 32, scr, lane); } }
.LBB0_895:
	s_cmp_eq_u32 s99, 1
	s_cbranch_scc0 .Lp4_tail_done
	s_mov_b32 s99, 2
	s_waitcnt vmcnt(0) lgkmcnt(0)
	s_barrier
	s_branch .Lp4_entry
